# 64 w_out transposes moved from the phase-3 hook to the phase-1 workgroups whose last-round item is a (tiny) cbias item; phase-3 hook now 96 workgroups
# baseline (speedup 1.0000x reference)
.LBB0_230:
	v_readlane_b32 s64, v209, 33
	v_readlane_b32 s62, v209, 35
	s_mov_b64 s[40:41], 0
	v_readlane_b32 s60, v209, 37
	v_readlane_b32 s65, v209, 34
	v_readlane_b32 s63, v209, 36
	v_readlane_b32 s61, v209, 38
	s_cmpk_eq_i32 s72, 0x200
	s_cbranch_scc0 .Lp3h_no
	s_sub_i32 s50, s60, 0x100
	s_cmpk_lt_u32 s50, 0x60
	s_cbranch_scc0 .Lp3h_no
	s_add_i32 s50, s50, 0x1a8
	s_movk_i32 s51, 0x200
	s_movk_i32 s52, 0x207
	s_movk_i32 s53, 0x440
	s_movk_i32 s54, 0x1e8
	s_add_u32 s46, s12, 8
	s_addc_u32 s47, s13, 0
	s_branch .Ltramp_p0a

.LBB0_361:
	s_cmpk_eq_i32 s72, 0x200
	s_cbranch_scc0 .Lp1h_no
	s_sub_i32 s50, s60, 0x180
	s_cmpk_lt_u32 s50, 0x80
	s_cbranch_scc0 .Lp1h_no
	s_add_i32 s50, s50, 0x168
	s_movk_i32 s51, 0x200
	s_movk_i32 s52, 0x227
	s_movk_i32 s53, 0x40
	s_movk_i32 s54, 0x1a8
	s_add_u32 s46, s12, 8
	s_addc_u32 s47, s13, 0
	s_branch .Lp0_head
